# attention loop: P pack + exchange ds_write moved before the PV23 MFMAs, K staging ds_write after MFMA 4 (LDS write drain under MFMAs)
# speedup vs baseline: 1.0085x; 1.0085x over previous
; #define SBAR() __builtin_amdgcn_sched_barrier(0)
; template <int DA, int DB> __device__ __forceinline__ void pv2_issue(PvT& T, int vb) {
;   T.t[0] = tr_read<v_rd_off(DA, 0, 0)>(vb); T.t[1] = tr_read<v_rd_off(DA, 0, 1)>(vb); T.t[2] = tr_read<v_rd_off(DA, 1, 0)>(vb); T.t[3] = tr_read<v_rd_off(DA, 1, 1)>(vb);
;   T.t[4] = tr_read<v_rd_off(DA, 2, 0)>(vb); T.t[5] = tr_read<v_rd_off(DA, 2, 1)>(vb); T.t[6] = tr_read<v_rd_off(DA, 3, 0)>(vb); T.t[7] = tr_read<v_rd_off(DA, 3, 1)>(vb);
;   T.t[8] = tr_read<v_rd_off(DB, 0, 0)>(vb); T.t[9] = tr_read<v_rd_off(DB, 0, 1)>(vb); T.t[10] = tr_read<v_rd_off(DB, 1, 0)>(vb); T.t[11] = tr_read<v_rd_off(DB, 1, 1)>(vb);
;   T.t[12] = tr_read<v_rd_off(DB, 2, 0)>(vb); T.t[13] = tr_read<v_rd_off(DB, 2, 1)>(vb); T.t[14] = tr_read<v_rd_off(DB, 3, 0)>(vb); T.t[15] = tr_read<v_rd_off(DB, 3, 1)>(vb);
; }
; __device__ __forceinline__ void pv2_mma(f32x16& oa, f32x16& ob, const PvT& T, bf16x8 pa0, bf16x8 pa1, bf16x8 pa2, bf16x8 pa3) {
;   asm volatile("s_waitcnt lgkmcnt(0)" ::: "memory"); SBAR();
;     ...
;   oa = __builtin_amdgcn_mfma_f32_32x32x16_bf16(pa0, PK(T.t[0], T.t[1]), oa, 0, 0, 0);
;   ob = __builtin_amdgcn_mfma_f32_32x32x16_bf16(pa0, PK(T.t[8], T.t[9]), ob, 0, 0, 0);
;   oa = __builtin_amdgcn_mfma_f32_32x32x16_bf16(pa1, PK(T.t[2], T.t[3]), oa, 0, 0, 0);
;   ob = __builtin_amdgcn_mfma_f32_32x32x16_bf16(pa1, PK(T.t[10], T.t[11]), ob, 0, 0, 0);
;   oa = __builtin_amdgcn_mfma_f32_32x32x16_bf16(pa2, PK(T.t[4], T.t[5]), oa, 0, 0, 0);
; __device__ __forceinline__ void attn_dv256_body(const bf16* __restrict__ Qb, const bf16* __restrict__ Kh, const bf16* __restrict__ Vh,
;                                                 float* __restrict__ Ob, int seq, float kmax, char* lds) {
;     ...
;   for (int j = 0; j < NT; ++j) {
;     const int b = j & 1;
;     PvT T;
;     pv2_issue<2, 3>(T, vb0 + (b ^ 1) * 32768);
;     QKH(pn, b ^ 1);
;     float ps = 0.f;
; #pragma unroll
;     for (int r = 0; r < 16; ++r) { pc[r] = __builtin_amdgcn_exp2f(fmaf(pc[r], C, mC)); ps += pc[r]; }
;     l_reg += ps;
;     pv2_mma(o[2], o[3], T, q0, q1, q2, q3);
;     pv2_issue<0, 1>(T, vb0 + (b ^ 1) * 32768);
;     bf16x8 own0, own1; PK4(pc, 0, own0); PK4(pc, 8, own1);
;     *(bf16x8*)(XC0 + b * 16384 + ((wid * 2 + 0) * 64 + lane) * 16) = own0; *(bf16x8*)(XC0 + b * 16384 + ((wid * 2 + 1) * 64 + lane) * 16) = own1;
;     KWRITE(b);
;     pv2_mma(o[0], o[1], T, q0, q1, q2, q3);
.LBB0_910:
	s_and_b32 s1, s7, 1
	s_xor_b32 s22, s1, 1
	s_lshl_b32 s13, s22, 15
	v_add_u32_e32 v247, s13, v207
	ds_read_b64_tr_b16 v[152:153], v247 offset:0x400
	ds_read_b64_tr_b16 v[154:155], v247 offset:0xc00
	ds_read_b64_tr_b16 v[156:157], v247 offset:0x1400
	ds_read_b64_tr_b16 v[158:159], v247 offset:0x1c00
	ds_read_b64_tr_b16 v[160:161], v247 offset:0x2400
	ds_read_b64_tr_b16 v[162:163], v247 offset:0x2c00
	ds_read_b64_tr_b16 v[210:211], v247 offset:0x3400
	ds_read_b64_tr_b16 v[212:213], v247 offset:0x3c00
	ds_read_b64_tr_b16 v[214:215], v247 offset:0x600
	ds_read_b64_tr_b16 v[216:217], v247 offset:0xe00
	ds_read_b64_tr_b16 v[218:219], v247 offset:0x1600
	ds_read_b64_tr_b16 v[220:221], v247 offset:0x1e00
	ds_read_b64_tr_b16 v[222:223], v247 offset:0x2600
	ds_read_b64_tr_b16 v[224:225], v247 offset:0x2e00
	v_lshl_add_u32 v246, s22, 14, v197
	ds_read_b64_tr_b16 v[226:227], v247 offset:0x3600
	v_fmamk_f32 v174, v64, 0x3e0293ee, v208
	v_add_u32_e32 v64, v246, v198
	ds_read_b64_tr_b16 v[228:229], v247 offset:0x3e00
	v_fmamk_f32 v175, v65, 0x3e0293ee, v208
	v_fmamk_f32 v181, v66, 0x3e0293ee, v208
	v_fmamk_f32 v182, v67, 0x3e0293ee, v208
	ds_read_b128 v[64:67], v64
	v_fmamk_f32 v238, v68, 0x3e0293ee, v208
	v_add_u32_e32 v68, v246, v199
	ds_read_b128 v[230:233], v68
	v_fmamk_f32 v239, v69, 0x3e0293ee, v208
	v_fmamk_f32 v240, v70, 0x3e0293ee, v208
	v_fmamk_f32 v241, v71, 0x3e0293ee, v208
	v_fmamk_f32 v242, v72, 0x3e0293ee, v208
	v_fmamk_f32 v243, v73, 0x3e0293ee, v208
	v_fmamk_f32 v244, v74, 0x3e0293ee, v208
	v_fmamk_f32 v245, v75, 0x3e0293ee, v208
	v_fmamk_f32 v248, v76, 0x3e0293ee, v208
	v_fmamk_f32 v249, v77, 0x3e0293ee, v208
	v_fmamk_f32 v250, v78, 0x3e0293ee, v208
	v_fmamk_f32 v173, v79, 0x3e0293ee, v208
	s_waitcnt lgkmcnt(1)
	v_mfma_f32_32x32x16_bf16 v[64:79], v[64:67], v[80:83], 0
	v_add_u32_e32 v234, v246, v200
	v_exp_f32_e32 v174, v174
	v_exp_f32_e32 v175, v175
	v_exp_f32_e32 v181, v181
	v_exp_f32_e32 v182, v182
	v_exp_f32_e32 v238, v238
	v_exp_f32_e32 v239, v239
	s_waitcnt lgkmcnt(0)
	v_mfma_f32_32x32x16_bf16 v[64:79], v[230:233], v[84:87], v[64:79]
	ds_read_b128 v[230:233], v234
	v_add_u32_e32 v234, v246, v201
	ds_read_b128 v[234:237], v234
	v_exp_f32_e32 v240, v240
	v_exp_f32_e32 v241, v241
	v_exp_f32_e32 v242, v242
	v_exp_f32_e32 v243, v243
	s_waitcnt lgkmcnt(1)
	v_mfma_f32_32x32x16_bf16 v[64:79], v[230:233], v[88:91], v[64:79]
	v_add_u32_e32 v230, v246, v202
	ds_read_b128 v[230:233], v230
	v_exp_f32_e32 v244, v244
	v_exp_f32_e32 v245, v245
	v_exp_f32_e32 v248, v248
	v_exp_f32_e32 v249, v249
	v_exp_f32_e32 v250, v250
	s_waitcnt lgkmcnt(1)
	v_mfma_f32_32x32x16_bf16 v[64:79], v[234:237], v[92:95], v[64:79]
	v_add_u32_e32 v234, v246, v203
	ds_read_b128 v[234:237], v234
	v_exp_f32_e32 v173, v173
	s_waitcnt lgkmcnt(1)
	v_mfma_f32_32x32x16_bf16 v[64:79], v[230:233], v[96:99], v[64:79]
	v_add_u32_e32 v230, v246, v204
	ds_read_b128 v[230:233], v230
	s_waitcnt lgkmcnt(1)
	v_mfma_f32_32x32x16_bf16 v[64:79], v[234:237], v[100:103], v[64:79]
	v_add_f32_e32 v235, 0, v174
	v_add_f32_e32 v235, v175, v235
	v_add_u32_e32 v234, v246, v206
	v_add_f32_e32 v235, v181, v235
	v_add_f32_e32 v246, v182, v235
	ds_read_b128 v[234:237], v234
	s_waitcnt lgkmcnt(0)
	s_waitcnt lgkmcnt(1)
	v_mfma_f32_32x32x16_bf16 v[64:79], v[230:233], v[104:107], v[64:79]
	v_add_f32_e32 v230, v238, v246
	v_add_f32_e32 v230, v239, v230
	v_add_f32_e32 v230, v240, v230
	v_add_f32_e32 v230, v241, v230
	v_add_f32_e32 v230, v242, v230
	v_add_f32_e32 v230, v243, v230
	v_add_f32_e32 v230, v244, v230
	s_waitcnt lgkmcnt(0)
	v_mfma_f32_32x32x16_bf16 v[64:79], v[234:237], v[108:111], v[64:79]
	v_add_f32_e32 v230, v245, v230
	v_add_f32_e32 v230, v248, v230
	v_add_f32_e32 v230, v249, v230
	v_add_f32_e32 v230, v250, v230
	v_add_f32_e32 v230, v173, v230
	v_add_f32_e32 v192, v192, v230
	v_cvt_pk_bf16_f32 v241, v240, v241
	v_cvt_pk_bf16_f32 v240, v238, v239
	v_cvt_pk_bf16_f32 v239, v181, v182
	v_cvt_pk_bf16_f32 v238, v174, v175
	v_cvt_pk_bf16_f32 v242, v242, v243
	v_cvt_pk_bf16_f32 v243, v244, v245
	v_cvt_pk_bf16_f32 v244, v248, v249
	v_cvt_pk_bf16_f32 v245, v250, v173
	s_lshl_b32 s1, s1, 14
	s_add_i32 s1, s1, 0
	s_add_i32 s35, s1, 0x18000
	s_add_i32 s1, s1, 0x10000
	v_permlane32_swap_b32_e32 v238, v240
	v_permlane32_swap_b32_e32 v239, v241
	v_add3_u32 v173, s35, v209, v205
	v_permlane32_swap_b32_e32 v242, v244
	v_permlane32_swap_b32_e32 v243, v245
	ds_write_b128 v173, v[238:241]
	ds_write_b128 v173, v[242:245] offset:1024
	v_mfma_f32_32x32x16_bf16 v[32:47], v[144:147], v[152:155], v[32:47]
	v_mfma_f32_32x32x16_bf16 v[48:63], v[144:147], v[214:217], v[48:63]
	v_mfma_f32_32x32x16_bf16 v[32:47], v[148:151], v[156:159], v[32:47]
	v_mfma_f32_32x32x16_bf16 v[48:63], v[148:151], v[218:221], v[48:63]
	v_add_u32_e32 v173, s1, v195
	s_waitcnt vmcnt(1)
	ds_write_b128 v173, v[136:139]
	v_add_u32_e32 v136, s1, v196
	s_waitcnt vmcnt(0)
	ds_write_b128 v136, v[140:143]
	v_mfma_f32_32x32x16_bf16 v[32:47], v[132:135], v[160:163], v[32:47]
	v_mfma_f32_32x32x16_bf16 v[48:63], v[132:135], v[222:225], v[48:63]
	v_mfma_f32_32x32x16_bf16 v[32:47], v[128:131], v[210:213], v[32:47]
	ds_read_b64_tr_b16 v[210:211], v247 offset:0
	ds_read_b64_tr_b16 v[212:213], v247 offset:0x800
	ds_read_b64_tr_b16 v[214:215], v247 offset:0x1000
	ds_read_b64_tr_b16 v[216:217], v247 offset:0x1800
	ds_read_b64_tr_b16 v[218:219], v247 offset:0x2000
	ds_read_b64_tr_b16 v[220:221], v247 offset:0x2800
	ds_read_b64_tr_b16 v[222:223], v247 offset:0x3000
	ds_read_b64_tr_b16 v[224:225], v247 offset:0x3800
	v_mfma_f32_32x32x16_bf16 v[48:63], v[128:131], v[226:229], v[48:63]
	ds_read_b64_tr_b16 v[226:227], v247 offset:0x200
	ds_read_b64_tr_b16 v[228:229], v247 offset:0xa00
	ds_read_b64_tr_b16 v[230:231], v247 offset:0x1200
	ds_read_b64_tr_b16 v[232:233], v247 offset:0x1a00
	ds_read_b64_tr_b16 v[234:235], v247 offset:0x2200
	ds_read_b64_tr_b16 v[236:237], v247 offset:0x2a00
	ds_read_b64_tr_b16 v[160:161], v247 offset:0x3200
	ds_read_b64_tr_b16 v[162:163], v247 offset:0x3a00
	s_waitcnt lgkmcnt(0)
	s_add_i32 s1, s13, 0
	s_add_i32 s13, s7, 3
	s_add_i32 s22, s7, 2
	v_add_u32_e32 v136, s1, v193
	v_add_u32_e32 v137, s1, v194
	s_min_u32 s1, s13, s0
	s_min_u32 s13, s22, s0
	s_lshl_b32 s1, s1, 6
	s_lshl_b32 s13, s13, 6
	s_waitcnt lgkmcnt(0)
	s_barrier
; #define KLOAD(k0) do { kr0 = St::ld8(&Kh[(long)((k0) + sr) * LDK + sc]); kr1 = St::ld8(&Kh[(long)((k0) + 32 + sr) * LDK + sc]); } while (0)
; #define VLOAD(k0) do { vr0 = St::ld8(&Vh[(long)((k0) + sr) * LDK + sc]); vr1 = St::ld8(&Vh[(long)((k0) + 32 + sr) * LDK + sc]); \
;     vr2 = St::ld8(&Vh[(long)((k0) + sr) * LDK + 128 + sc]); vr3 = St::ld8(&Vh[(long)((k0) + 32 + sr) * LDK + 128 + sc]); } while (0)
; #define VWRITE(b) do { *(bf16x8*)(V_lds + ((b) * 2) * 16384 + vst0) = vr0; *(bf16x8*)(V_lds + ((b) * 2) * 16384 + vst1) = vr1; \
;     *(bf16x8*)(V_lds + ((b) * 2 + 1) * 16384 + vst1) = vr2; *(bf16x8*)(V_lds + ((b) * 2 + 1) * 16384 + vst0) = vr3; } while (0)
; __device__ __forceinline__ void attn_dv256_body(const bf16* __restrict__ Qb, const bf16* __restrict__ Kh, const bf16* __restrict__ Vh,
;                                                 float* __restrict__ Ob, int seq, float kmax, char* lds) {
;     ...
;     pv2_mma(o[0], o[1], T, q0, q1, q2, q3);
;     __syncthreads();
;     VWRITE(b ^ 1);
;     { const int kt = (j + 3 < NT) ? j + 3 : NT - 1, vt = (j + 2 < NT) ? j + 2 : NT - 1; KLOAD(kt * KVBLK); VLOAD(vt * KVBLK); }
;     q0 = own0; q1 = own1;
;     q2 = *(const bf16x8*)(XC0 + b * 16384 + (((wid ^ 4) * 2 + 0) * 64 + lane) * 16); q3 = *(const bf16x8*)(XC0 + b * 16384 + (((wid ^ 4) * 2 + 1) * 64 + lane) * 16);
;     pc = pn;
;   }
;   { PvT T; const int vl = vb0 + ((NT - 1) & 1) * 32768;
;     pv2_issue<2, 3>(T, vl); pv2_mma(o[2], o[3], T, q0, q1, q2, q3); pv2_issue<0, 1>(T, vl); pv2_mma(o[0], o[1], T, q0, q1, q2, q3); }
;   l_reg += __shfl_xor(l_reg, 32);
;   if (hi == 0) LI[kh * 128 + rg * 32 + r32] = l_reg;
	ds_write_b128 v136, v[116:119]
	ds_write_b128 v137, v[112:115]
	v_add_u32_e32 v112, s1, v189
	v_add_u32_e32 v114, s1, v190
	v_add_u32_e32 v116, s13, v189
	ds_write_b128 v137, v[120:123] offset:16384
	ds_write_b128 v136, v[124:127] offset:16384
	v_add_u32_e32 v117, s13, v190
	v_mad_i64_i32 v[112:113], s[22:23], v112, s93, v[166:167]
	v_mad_i64_i32 v[114:115], s[22:23], v114, s93, v[166:167]
	v_mad_i64_i32 v[120:121], s[22:23], v116, s93, v[168:169]
	v_mad_i64_i32 v[124:125], s[22:23], v117, s93, v[168:169]
	global_load_dwordx4 v[136:139], v[112:113], off
	global_load_dwordx4 v[140:143], v[114:115], off
	s_nop 0
	global_load_dwordx4 v[112:115], v[124:125], off
	global_load_dwordx4 v[116:119], v[120:121], off
	s_nop 0
	global_load_dwordx4 v[120:123], v[120:121], off offset:256
	v_mfma_f32_32x32x16_bf16 v[0:15], v[144:147], v[210:213], v[0:15]
	global_load_dwordx4 v[124:127], v[124:125], off offset:256
	s_add_i32 s7, s7, 1
	s_cmp_eq_u32 s6, s7
	v_mfma_f32_32x32x16_bf16 v[16:31], v[144:147], v[226:229], v[16:31]
	v_mov_b32_e32 v144, v238
	v_mov_b32_e32 v145, v239
	v_mov_b32_e32 v146, v240
	v_mov_b32_e32 v147, v241
	v_mfma_f32_32x32x16_bf16 v[0:15], v[148:151], v[214:217], v[0:15]
	v_mfma_f32_32x32x16_bf16 v[16:31], v[148:151], v[230:233], v[16:31]
	v_mov_b32_e32 v149, v243
	v_mov_b32_e32 v150, v244
	v_mov_b32_e32 v151, v245
	v_mfma_f32_32x32x16_bf16 v[0:15], v[132:135], v[218:221], v[0:15]
	v_mfma_f32_32x32x16_bf16 v[16:31], v[132:135], v[234:237], v[16:31]
	v_bitop3_b32 v132, v209, s95, v205 bitop3:0x36
	v_add_u32_e32 v148, s35, v132
	v_mfma_f32_32x32x16_bf16 v[0:15], v[128:131], v[222:225], v[0:15]
	v_mfma_f32_32x32x16_bf16 v[16:31], v[128:131], v[160:163], v[16:31]
	ds_read_b128 v[132:135], v148
	ds_read_b128 v[128:131], v148 offset:1024
	v_mov_b32_e32 v148, v242
	s_cbranch_scc0 .LBB0_910
	v_mov_b32_e32 v152, v238
	v_mov_b32_e32 v153, v239
	v_mov_b32_e32 v154, v240
	v_mov_b32_e32 v155, v241
	v_mov_b32_e32 v156, v242
	v_mov_b32_e32 v157, v243
	v_mov_b32_e32 v158, v244
	v_mov_b32_e32 v159, v245
	v_add_u32_e32 v96, 0x8000, v207
	ds_read_b64_tr_b16 v[64:65], v96 offset:0x400
	ds_read_b64_tr_b16 v[66:67], v96 offset:0xc00
	ds_read_b64_tr_b16 v[68:69], v96 offset:0x1400
	ds_read_b64_tr_b16 v[70:71], v96 offset:0x1c00
	ds_read_b64_tr_b16 v[72:73], v96 offset:0x2400
	ds_read_b64_tr_b16 v[74:75], v96 offset:0x2c00
	ds_read_b64_tr_b16 v[76:77], v96 offset:0x3400
	ds_read_b64_tr_b16 v[78:79], v96 offset:0x3c00
	ds_read_b64_tr_b16 v[80:81], v96 offset:0x600
	ds_read_b64_tr_b16 v[82:83], v96 offset:0xe00
	ds_read_b64_tr_b16 v[84:85], v96 offset:0x1600
	ds_read_b64_tr_b16 v[86:87], v96 offset:0x1e00
	ds_read_b64_tr_b16 v[88:89], v96 offset:0x2600
	ds_read_b64_tr_b16 v[90:91], v96 offset:0x2e00
	ds_read_b64_tr_b16 v[92:93], v96 offset:0x3600
	ds_read_b64_tr_b16 v[94:95], v96 offset:0x3e00
	s_waitcnt lgkmcnt(0)
	s_nop 0
	v_mfma_f32_32x32x16_bf16 v[32:47], v[152:155], v[64:67], v[32:47]
	ds_read_b64_tr_b16 v[64:65], v96 offset:0
	ds_read_b64_tr_b16 v[66:67], v96 offset:0x800
	v_mfma_f32_32x32x16_bf16 v[48:63], v[152:155], v[80:83], v[48:63]
	v_mfma_f32_32x32x16_bf16 v[32:47], v[156:159], v[68:71], v[32:47]
	ds_read_b64_tr_b16 v[68:69], v96 offset:0x1000
	ds_read_b64_tr_b16 v[70:71], v96 offset:0x1800
	v_mfma_f32_32x32x16_bf16 v[48:63], v[156:159], v[84:87], v[48:63]
	s_waitcnt lgkmcnt(1)
	v_mfma_f32_32x32x16_bf16 v[32:47], v[132:135], v[72:75], v[32:47]
	ds_read_b64_tr_b16 v[72:73], v96 offset:0x2000
	ds_read_b64_tr_b16 v[74:75], v96 offset:0x2800
	v_mfma_f32_32x32x16_bf16 v[48:63], v[132:135], v[88:91], v[48:63]
	s_waitcnt lgkmcnt(0)
	v_mfma_f32_32x32x16_bf16 v[32:47], v[128:131], v[76:79], v[32:47]
	ds_read_b64_tr_b16 v[76:77], v96 offset:0x3000
	ds_read_b64_tr_b16 v[78:79], v96 offset:0x3800
	ds_read_b64_tr_b16 v[80:81], v96 offset:0x200
	ds_read_b64_tr_b16 v[82:83], v96 offset:0xa00
	ds_read_b64_tr_b16 v[84:85], v96 offset:0x1200
	ds_read_b64_tr_b16 v[86:87], v96 offset:0x1a00
	ds_read_b64_tr_b16 v[88:89], v96 offset:0x2200
	v_mfma_f32_32x32x16_bf16 v[48:63], v[128:131], v[92:95], v[48:63]
	ds_read_b64_tr_b16 v[90:91], v96 offset:0x2a00
	ds_read_b64_tr_b16 v[92:93], v96 offset:0x3200
	ds_read_b64_tr_b16 v[94:95], v96 offset:0x3a00
	s_waitcnt lgkmcnt(0)
	v_mfma_f32_32x32x16_bf16 v[0:15], v[152:155], v[64:67], v[0:15]
	ds_bpermute_b32 v66, v188, v192
	v_cmp_gt_u32_e32 vcc, 32, v191
	v_lshlrev_b32_e32 v65, 2, v185
	v_lshlrev_b32_e32 v64, 2, v186
	v_mfma_f32_32x32x16_bf16 v[16:31], v[152:155], v[80:83], v[16:31]
	v_mfma_f32_32x32x16_bf16 v[0:15], v[156:159], v[68:71], v[0:15]
	v_mfma_f32_32x32x16_bf16 v[16:31], v[156:159], v[84:87], v[16:31]
	v_mfma_f32_32x32x16_bf16 v[0:15], v[132:135], v[72:75], v[0:15]
	v_mfma_f32_32x32x16_bf16 v[16:31], v[132:135], v[88:91], v[16:31]
	v_mfma_f32_32x32x16_bf16 v[0:15], v[128:131], v[76:79], v[0:15]
	v_mfma_f32_32x32x16_bf16 v[16:31], v[128:131], v[92:95], v[16:31]
	s_and_saveexec_b64 s[0:1], vcc
	s_cbranch_execz .LBB0_913
	s_add_i32 s6, 0, 0x20000
	v_lshl_add_u32 v67, v187, 9, s6
	v_add3_u32 v67, v67, v65, v64
	s_waitcnt lgkmcnt(0)
	v_add_f32_e32 v66, v192, v66
	ds_write_b32 v67, v66
